# norm2 phase (P7): next iteration's x rows software-prefetched into spare VGPRs (load latency overlapped with the current rows' normalisation)
# speedup vs baseline: 1.0080x; 1.0007x over previous
.LBB0_892:
	s_or_b64 exec, exec, s[36:37]
	s_cmpk_lt_i32 s2, 0x800
	s_cselect_b64 s[36:37], -1, 0
	s_cmpk_gt_i32 s2, 0x7ff
	s_waitcnt lgkmcnt(0)
	s_barrier
	s_cbranch_scc1 .LBB0_895
	v_and_b32_e32 v0, 63, v132
	v_mbcnt_lo_u32_b32 v2, -1, 0
	v_or_b32_e32 v6, 64, v0
	v_or_b32_e32 v10, 0x80, v0
	v_or_b32_e32 v14, 0xc0, v0
	s_add_i32 s4, 0, 0x240a0
	v_mbcnt_hi_u32_b32 v19, -1, v2
	v_mov_b32_e32 v1, 0
	v_lshlrev_b32_e32 v4, 2, v0
	v_lshlrev_b32_e32 v8, 2, v6
	v_lshlrev_b32_e32 v12, 2, v10
	v_lshlrev_b32_e32 v16, 2, v14
	v_mov_b32_e32 v3, s4
	s_add_i32 s4, 0, 0x24070
	v_and_b32_e32 v2, 64, v19
	s_lshl_b32 s3, s2, 4
	s_lshl_b32 s13, s40, 4
	v_mov_b32_e32 v18, s4
	s_mov_b64 s[6:7], 0x2283000
	s_mov_b64 s[8:9], 0x2284000
	s_mov_b64 s[10:11], 0x2400000
	v_lshlrev_b32_e32 v0, 4, v0
	s_movk_i32 s14, 0x1000
	v_add_u32_e32 v20, 64, v2
	v_xor_b32_e32 v21, 32, v19
	v_xor_b32_e32 v22, 16, v19
	v_xor_b32_e32 v23, 8, v19
	v_xor_b32_e32 v24, 4, v19
	v_xor_b32_e32 v25, 2, v19
	v_xor_b32_e32 v26, 1, v19
	s_mov_b32 s12, 0x3a800000
	v_mov_b32_e32 v2, 0x358637bd
	s_mov_b32 s15, 0x800000
	v_lshlrev_b32_e32 v4, 1, v4
	v_mov_b32_e32 v5, v1
	v_lshlrev_b32_e32 v6, 4, v6
	v_mov_b32_e32 v7, v1
	v_lshlrev_b32_e32 v8, 1, v8
	v_mov_b32_e32 v9, v1
	v_lshlrev_b32_e32 v10, 4, v10
	v_mov_b32_e32 v11, v1
	v_lshlrev_b32_e32 v12, 1, v12
	v_mov_b32_e32 v13, v1
	v_lshlrev_b32_e32 v14, 4, v14
	v_mov_b32_e32 v15, v1
	v_lshlrev_b32_e32 v16, 1, v16
	v_mov_b32_e32 v17, v1
	s_mov_b32 s16, s2
	s_lshl_b32 s98, s40, 16
	s_mov_b32 s99, 0
	s_mov_b64 s[100:101], 0x1000
.LBB0_894:
	v_mov_b32_e32 v27, v132
	v_cmp_lt_i32_e32 vcc, v21, v20
	ds_read_b128 v[28:31], v3
	ds_read_b64 v[32:33], v18
	v_cndmask_b32_e32 v34, v19, v21, vcc
	v_cmp_lt_i32_e32 vcc, v22, v20
	v_ashrrev_i32_e32 v27, 5, v27
	v_and_b32_e32 v27, -2, v27
	v_cndmask_b32_e32 v35, v19, v22, vcc
	v_cmp_lt_i32_e32 vcc, v23, v20
	v_lshlrev_b32_e32 v133, 2, v34
	v_add_u32_e32 v34, s3, v27
	v_cndmask_b32_e32 v36, v19, v23, vcc
	v_cmp_lt_i32_e32 vcc, v24, v20
	v_lshlrev_b32_e32 v150, 2, v35
	v_ashrrev_i32_e32 v35, 31, v34
	v_cndmask_b32_e32 v37, v19, v24, vcc
	v_cmp_lt_i32_e32 vcc, v25, v20
	v_lshlrev_b32_e32 v151, 2, v36
	v_lshlrev_b32_e32 v152, 2, v37
	v_ashrrev_i32_e32 v27, 12, v34
	v_lshlrev_b64 v[36:37], 12, v[34:35]
	v_cndmask_b32_e32 v38, v19, v25, vcc
	v_cmp_lt_i32_e32 vcc, v26, v20
	v_mul_i32_i24_e32 v48, 0x1800, v27
	s_waitcnt lgkmcnt(0)
	v_lshl_add_u64 v[28:29], v[28:29], 0, v[36:37]
	v_cndmask_b32_e32 v39, v19, v26, vcc
	v_lshlrev_b64 v[34:35], 11, v[34:35]
	v_lshl_add_u64 v[50:51], v[32:33], 0, v[0:1]
	v_ashrrev_i32_e32 v49, 31, v48
	v_lshl_add_u64 v[62:63], v[28:29], 0, v[0:1]
	v_mov_b32_e32 v156, v62
	v_mov_b32_e32 v157, v63
	v_lshlrev_b32_e32 v153, 2, v38
	v_lshlrev_b32_e32 v154, 2, v39
	v_lshl_add_u64 v[52:53], v[30:31], 0, v[34:35]
	flat_load_dwordx4 v[32:35], v[50:51]
	flat_load_dwordx4 v[36:39], v[50:51] offset:1024
	flat_load_dwordx4 v[40:43], v[50:51] offset:2048
	flat_load_dwordx4 v[44:47], v[50:51] offset:3072
	v_lshl_add_u64 v[54:55], v[48:49], 2, v[30:31]
	flat_load_dwordx4 v[28:31], v[62:63] nt
	flat_load_dwordx4 v[48:51], v[62:63] offset:1024 nt
	v_add_co_u32_e32 v80, vcc, s14, v62
	v_lshl_add_u64 v[60:61], v[52:53], 0, s[10:11]
	v_lshl_add_u64 v[76:77], v[54:55], 0, s[6:7]
	v_lshl_add_u64 v[78:79], v[54:55], 0, s[8:9]
	flat_load_dwordx4 v[52:55], v[62:63] offset:2048 nt
	flat_load_dwordx4 v[56:59], v[62:63] offset:3072 nt
	v_addc_co_u32_e32 v81, vcc, 0, v63, vcc
	v_lshl_add_u64 v[108:109], v[60:61], 0, v[4:5]
	v_lshl_add_u64 v[110:111], v[60:61], 0, v[8:9]
	v_lshl_add_u64 v[112:113], v[60:61], 0, v[12:13]
	v_lshl_add_u64 v[114:115], v[60:61], 0, v[16:17]
	flat_load_dwordx4 v[60:63], v[80:81] nt
	flat_load_dwordx4 v[64:67], v[80:81] offset:1024 nt
	flat_load_dwordx4 v[68:71], v[80:81] offset:2048 nt
	flat_load_dwordx4 v[72:75], v[80:81] offset:3072 nt
	v_lshl_add_u64 v[96:97], v[76:77], 0, v[0:1]
	v_lshl_add_u64 v[98:99], v[78:79], 0, v[0:1]
	v_lshl_add_u64 v[100:101], v[78:79], 0, v[6:7]
	v_lshl_add_u64 v[102:103], v[78:79], 0, v[10:11]
	v_lshl_add_u64 v[104:105], v[78:79], 0, v[14:15]
	v_lshl_add_u64 v[116:117], v[76:77], 0, v[6:7]
	v_lshl_add_u64 v[118:119], v[76:77], 0, v[10:11]
	v_lshl_add_u64 v[120:121], v[76:77], 0, v[14:15]
	flat_load_dwordx4 v[76:79], v[98:99]
	flat_load_dwordx4 v[80:83], v[100:101]
	flat_load_dwordx4 v[84:87], v[102:103]
	flat_load_dwordx4 v[88:91], v[104:105]
	flat_load_dwordx4 v[92:95], v[96:97]
	s_nop 0
	flat_load_dwordx4 v[96:99], v[116:117]
	flat_load_dwordx4 v[100:103], v[118:119]
	flat_load_dwordx4 v[104:107], v[120:121]
	s_add_i32 s16, s16, s40
	s_add_i32 s3, s3, s13
	s_cmpk_gt_i32 s16, 0x7ff
	s_waitcnt vmcnt(0) lgkmcnt(0)
	s_cbranch_scc1 .Lnpf_skip_a
	v_lshl_add_u64 v[156:157], v[156:157], 0, s[98:99]
	v_lshl_add_u64 v[158:159], v[156:157], 0, s[100:101]
	global_load_dwordx4 v[160:163], v[156:157], off nt
	global_load_dwordx4 v[164:167], v[156:157], off offset:1024 nt
	global_load_dwordx4 v[168:171], v[156:157], off offset:2048 nt
	global_load_dwordx4 v[172:175], v[156:157], off offset:3072 nt
	global_load_dwordx4 v[176:179], v[158:159], off nt
	global_load_dwordx4 v[180:183], v[158:159], off offset:1024 nt
	global_load_dwordx4 v[184:187], v[158:159], off offset:2048 nt
	global_load_dwordx4 v[188:191], v[158:159], off offset:3072 nt
.Lnpf_skip_a:
	v_mov_b32_e32 v118, v29
	v_mov_b32_e32 v119, v49
	v_mov_b32_e32 v116, v28
	v_mov_b32_e32 v117, v48
	v_pk_mul_f32 v[118:119], v[118:119], v[118:119]
	v_mov_b32_e32 v120, v30
	v_mov_b32_e32 v126, v53
	v_mov_b32_e32 v127, v57
	v_mov_b32_e32 v124, v52
	v_mov_b32_e32 v125, v56
	v_pk_mul_f32 v[126:127], v[126:127], v[126:127]
	v_mov_b32_e32 v136, v61
	v_mov_b32_e32 v137, v65
	v_mov_b32_e32 v134, v60
	v_mov_b32_e32 v135, v64
	v_mov_b32_e32 v144, v69
	v_mov_b32_e32 v145, v73
	v_pk_fma_f32 v[116:117], v[116:117], v[116:117], v[118:119]
	v_pk_mul_f32 v[118:119], v[136:137], v[136:137]
	v_mov_b32_e32 v121, v50
	v_mov_b32_e32 v128, v54
	v_mov_b32_e32 v129, v58
	v_mov_b32_e32 v138, v62
	v_mov_b32_e32 v139, v66
	v_mov_b32_e32 v142, v68
	v_mov_b32_e32 v143, v72
	v_pk_fma_f32 v[124:125], v[124:125], v[124:125], v[126:127]
	v_pk_mul_f32 v[126:127], v[144:145], v[144:145]
	v_pk_fma_f32 v[118:119], v[134:135], v[134:135], v[118:119]
	v_mov_b32_e32 v122, v31
	v_mov_b32_e32 v123, v51
	v_mov_b32_e32 v140, v63
	v_mov_b32_e32 v141, v67
	v_mov_b32_e32 v146, v70
	v_mov_b32_e32 v147, v74
	v_pk_fma_f32 v[116:117], v[120:121], v[120:121], v[116:117]
	v_pk_fma_f32 v[120:121], v[128:129], v[128:129], v[124:125]
	v_pk_fma_f32 v[124:125], v[142:143], v[142:143], v[126:127]
	v_pk_fma_f32 v[118:119], v[138:139], v[138:139], v[118:119]
	v_mov_b32_e32 v130, v55
	v_mov_b32_e32 v131, v59
	v_mov_b32_e32 v148, v71
	v_mov_b32_e32 v149, v75
	v_pk_fma_f32 v[116:117], v[122:123], v[122:123], v[116:117]
	v_pk_fma_f32 v[122:123], v[146:147], v[146:147], v[124:125]
	v_pk_fma_f32 v[118:119], v[140:141], v[140:141], v[118:119]
	v_pk_fma_f32 v[120:121], v[130:131], v[130:131], v[120:121]
	v_pk_fma_f32 v[122:123], v[148:149], v[148:149], v[122:123]
	v_mov_b32_e32 v125, v116
	v_mov_b32_e32 v124, v118
	v_mov_b32_e32 v116, v119
	v_mov_b32_e32 v127, v120
	v_mov_b32_e32 v126, v122
	v_pk_add_f32 v[116:117], v[124:125], v[116:117]
	v_mov_b32_e32 v120, v123
	v_pk_add_f32 v[116:117], v[116:117], v[126:127]
	v_pk_add_f32 v[76:77], v[76:77], 1.0 op_sel_hi:[1,0]
	v_pk_add_f32 v[116:117], v[116:117], v[120:121]
	ds_bpermute_b32 v119, v133, v117
	ds_bpermute_b32 v118, v133, v116
	v_pk_add_f32 v[78:79], v[78:79], 1.0 op_sel_hi:[1,0]
	v_pk_add_f32 v[80:81], v[80:81], 1.0 op_sel_hi:[1,0]
	v_pk_add_f32 v[82:83], v[82:83], 1.0 op_sel_hi:[1,0]
	v_pk_add_f32 v[84:85], v[84:85], 1.0 op_sel_hi:[1,0]
	s_waitcnt lgkmcnt(0)
	v_pk_add_f32 v[116:117], v[116:117], v[118:119]
	ds_bpermute_b32 v119, v150, v117
	ds_bpermute_b32 v118, v150, v116
	v_pk_add_f32 v[86:87], v[86:87], 1.0 op_sel_hi:[1,0]
	v_pk_add_f32 v[88:89], v[88:89], 1.0 op_sel_hi:[1,0]
	v_pk_add_f32 v[90:91], v[90:91], 1.0 op_sel_hi:[1,0]
	s_waitcnt lgkmcnt(0)
	v_pk_add_f32 v[116:117], v[116:117], v[118:119]
	ds_bpermute_b32 v119, v151, v117
	ds_bpermute_b32 v118, v151, v116
	s_waitcnt lgkmcnt(0)
	v_pk_add_f32 v[116:117], v[116:117], v[118:119]
	ds_bpermute_b32 v119, v152, v117
	ds_bpermute_b32 v118, v152, v116
	s_waitcnt lgkmcnt(0)
	v_pk_add_f32 v[116:117], v[116:117], v[118:119]
	ds_bpermute_b32 v119, v153, v117
	ds_bpermute_b32 v118, v153, v116
	s_waitcnt lgkmcnt(0)
	v_pk_add_f32 v[116:117], v[116:117], v[118:119]
	ds_bpermute_b32 v119, v154, v117
	ds_bpermute_b32 v118, v154, v116
	s_waitcnt lgkmcnt(0)
	v_pk_add_f32 v[116:117], v[116:117], v[118:119]
	s_nop 0
	v_pk_fma_f32 v[116:117], v[116:117], s[12:13], v[2:3] op_sel_hi:[1,0,0]
	s_nop 0
	v_mul_f32_e32 v27, 0x4b800000, v117
	v_cmp_gt_f32_e64 s[4:5], s15, v117
	v_mul_f32_e32 v118, 0x4b800000, v116
	v_cmp_gt_f32_e32 vcc, s15, v116
	v_cndmask_b32_e64 v27, v117, v27, s[4:5]
	v_rsq_f32_e32 v27, v27
	v_cndmask_b32_e32 v116, v116, v118, vcc
	v_rsq_f32_e32 v117, v116
	v_mul_f32_e32 v116, 0x45800000, v27
	v_cndmask_b32_e64 v116, v27, v116, s[4:5]
	v_mul_f32_e32 v118, 0x45800000, v117
	v_cndmask_b32_e32 v118, v117, v118, vcc
	v_pk_mul_f32 v[28:29], v[28:29], v[116:117] op_sel_hi:[1,0]
	v_pk_mul_f32 v[30:31], v[30:31], v[116:117] op_sel_hi:[1,0]
	v_pk_mul_f32 v[60:61], v[60:61], v[118:119] op_sel_hi:[1,0]
	v_pk_mul_f32 v[62:63], v[62:63], v[118:119] op_sel_hi:[1,0]
	v_pk_mul_f32 v[48:49], v[48:49], v[116:117] op_sel_hi:[1,0]
	v_pk_mul_f32 v[50:51], v[50:51], v[116:117] op_sel_hi:[1,0]
	v_pk_mul_f32 v[64:65], v[64:65], v[118:119] op_sel_hi:[1,0]
	v_pk_mul_f32 v[66:67], v[66:67], v[118:119] op_sel_hi:[1,0]
	v_pk_mul_f32 v[52:53], v[52:53], v[116:117] op_sel_hi:[1,0]
	v_pk_mul_f32 v[54:55], v[54:55], v[116:117] op_sel_hi:[1,0]
	v_pk_mul_f32 v[68:69], v[68:69], v[118:119] op_sel_hi:[1,0]
	v_pk_mul_f32 v[70:71], v[70:71], v[118:119] op_sel_hi:[1,0]
	v_pk_mul_f32 v[56:57], v[56:57], v[116:117] op_sel_hi:[1,0]
	v_pk_mul_f32 v[58:59], v[58:59], v[116:117] op_sel_hi:[1,0]
	v_pk_mul_f32 v[72:73], v[72:73], v[118:119] op_sel_hi:[1,0]
	v_pk_mul_f32 v[74:75], v[74:75], v[118:119] op_sel_hi:[1,0]
	v_pk_mul_f32 v[28:29], v[32:33], v[28:29]
	v_pk_mul_f32 v[30:31], v[34:35], v[30:31]
	v_pk_mul_f32 v[32:33], v[32:33], v[60:61]
	v_pk_mul_f32 v[34:35], v[34:35], v[62:63]
	v_pk_mul_f32 v[48:49], v[48:49], v[36:37]
	v_pk_mul_f32 v[50:51], v[50:51], v[38:39]
	v_pk_mul_f32 v[36:37], v[64:65], v[36:37]
	v_pk_mul_f32 v[38:39], v[66:67], v[38:39]
	v_pk_mul_f32 v[52:53], v[52:53], v[40:41]
	v_pk_mul_f32 v[54:55], v[54:55], v[42:43]
	v_pk_mul_f32 v[40:41], v[68:69], v[40:41]
	v_pk_mul_f32 v[42:43], v[70:71], v[42:43]
	v_pk_mul_f32 v[56:57], v[56:57], v[44:45]
	v_pk_mul_f32 v[58:59], v[58:59], v[46:47]
	v_pk_mul_f32 v[44:45], v[72:73], v[44:45]
	v_pk_mul_f32 v[46:47], v[74:75], v[46:47]
	v_pk_fma_f32 v[28:29], v[28:29], v[76:77], v[92:93]
	v_pk_fma_f32 v[30:31], v[30:31], v[78:79], v[94:95]
	v_pk_fma_f32 v[32:33], v[76:77], v[32:33], v[92:93]
	v_pk_fma_f32 v[34:35], v[34:35], v[78:79], v[94:95]
	v_pk_fma_f32 v[48:49], v[48:49], v[80:81], v[96:97]
	v_pk_fma_f32 v[50:51], v[50:51], v[82:83], v[98:99]
	v_pk_fma_f32 v[36:37], v[36:37], v[80:81], v[96:97]
	v_pk_fma_f32 v[38:39], v[38:39], v[82:83], v[98:99]
	v_pk_fma_f32 v[52:53], v[52:53], v[84:85], v[100:101]
	v_pk_fma_f32 v[54:55], v[54:55], v[86:87], v[102:103]
	v_pk_fma_f32 v[40:41], v[40:41], v[84:85], v[100:101]
	v_pk_fma_f32 v[42:43], v[42:43], v[86:87], v[102:103]
	v_pk_fma_f32 v[56:57], v[56:57], v[88:89], v[104:105]
	v_pk_fma_f32 v[58:59], v[58:59], v[90:91], v[106:107]
	v_pk_fma_f32 v[44:45], v[44:45], v[88:89], v[104:105]
	v_pk_fma_f32 v[46:47], v[46:47], v[90:91], v[106:107]
	v_cvt_pk_bf16_f32 v28, v28, v29
	v_cvt_pk_bf16_f32 v29, v30, v31
	v_cvt_pk_bf16_f32 v30, v32, v33
	v_cvt_pk_bf16_f32 v31, v34, v35
	v_cvt_pk_bf16_f32 v32, v48, v49
	v_cvt_pk_bf16_f32 v33, v50, v51
	v_cvt_pk_bf16_f32 v34, v36, v37
	v_cvt_pk_bf16_f32 v35, v38, v39
	v_cvt_pk_bf16_f32 v36, v52, v53
	v_cvt_pk_bf16_f32 v37, v54, v55
	v_cvt_pk_bf16_f32 v38, v40, v41
	v_cvt_pk_bf16_f32 v39, v42, v43
	v_cvt_pk_bf16_f32 v40, v56, v57
	v_cvt_pk_bf16_f32 v41, v58, v59
	v_cvt_pk_bf16_f32 v42, v44, v45
	v_cvt_pk_bf16_f32 v43, v46, v47
	flat_store_dwordx2 v[108:109], v[28:29]
	flat_store_dwordx2 v[108:109], v[30:31] offset:2048
	flat_store_dwordx2 v[110:111], v[32:33]
	flat_store_dwordx2 v[110:111], v[34:35] offset:2048
	flat_store_dwordx2 v[112:113], v[36:37]
	flat_store_dwordx2 v[112:113], v[38:39] offset:2048
	flat_store_dwordx2 v[114:115], v[40:41]
	flat_store_dwordx2 v[114:115], v[42:43] offset:2048
	s_cbranch_scc1 .LBB0_895
.Lnpf_loop:
	v_mov_b32_e32 v27, v132
	v_cmp_lt_i32_e32 vcc, v21, v20
	ds_read_b128 v[28:31], v3
	ds_read_b64 v[32:33], v18
	v_cndmask_b32_e32 v34, v19, v21, vcc
	v_cmp_lt_i32_e32 vcc, v22, v20
	v_ashrrev_i32_e32 v27, 5, v27
	v_and_b32_e32 v27, -2, v27
	v_cndmask_b32_e32 v35, v19, v22, vcc
	v_cmp_lt_i32_e32 vcc, v23, v20
	v_lshlrev_b32_e32 v133, 2, v34
	v_add_u32_e32 v34, s3, v27
	v_cndmask_b32_e32 v36, v19, v23, vcc
	v_cmp_lt_i32_e32 vcc, v24, v20
	v_lshlrev_b32_e32 v150, 2, v35
	v_ashrrev_i32_e32 v35, 31, v34
	v_cndmask_b32_e32 v37, v19, v24, vcc
	v_cmp_lt_i32_e32 vcc, v25, v20
	v_lshlrev_b32_e32 v151, 2, v36
	v_lshlrev_b32_e32 v152, 2, v37
	v_ashrrev_i32_e32 v27, 12, v34
	v_lshlrev_b64 v[36:37], 12, v[34:35]
	v_cndmask_b32_e32 v38, v19, v25, vcc
	v_cmp_lt_i32_e32 vcc, v26, v20
	v_mul_i32_i24_e32 v48, 0x1800, v27
	s_waitcnt lgkmcnt(0)
	v_lshl_add_u64 v[28:29], v[28:29], 0, v[36:37]
	v_cndmask_b32_e32 v39, v19, v26, vcc
	v_lshlrev_b64 v[34:35], 11, v[34:35]
	v_lshl_add_u64 v[50:51], v[32:33], 0, v[0:1]
	v_ashrrev_i32_e32 v49, 31, v48
	v_lshl_add_u64 v[62:63], v[28:29], 0, v[0:1]
	v_lshlrev_b32_e32 v153, 2, v38
	v_lshlrev_b32_e32 v154, 2, v39
	v_lshl_add_u64 v[52:53], v[30:31], 0, v[34:35]
	flat_load_dwordx4 v[32:35], v[50:51]
	flat_load_dwordx4 v[36:39], v[50:51] offset:1024
	flat_load_dwordx4 v[40:43], v[50:51] offset:2048
	flat_load_dwordx4 v[44:47], v[50:51] offset:3072
	v_lshl_add_u64 v[54:55], v[48:49], 2, v[30:31]
	v_add_co_u32_e32 v80, vcc, s14, v62
	v_lshl_add_u64 v[60:61], v[52:53], 0, s[10:11]
	v_lshl_add_u64 v[76:77], v[54:55], 0, s[6:7]
	v_lshl_add_u64 v[78:79], v[54:55], 0, s[8:9]
	v_addc_co_u32_e32 v81, vcc, 0, v63, vcc
	v_lshl_add_u64 v[108:109], v[60:61], 0, v[4:5]
	v_lshl_add_u64 v[110:111], v[60:61], 0, v[8:9]
	v_lshl_add_u64 v[112:113], v[60:61], 0, v[12:13]
	v_lshl_add_u64 v[114:115], v[60:61], 0, v[16:17]
	v_lshl_add_u64 v[96:97], v[76:77], 0, v[0:1]
	v_lshl_add_u64 v[98:99], v[78:79], 0, v[0:1]
	v_lshl_add_u64 v[100:101], v[78:79], 0, v[6:7]
	v_lshl_add_u64 v[102:103], v[78:79], 0, v[10:11]
	v_lshl_add_u64 v[104:105], v[78:79], 0, v[14:15]
	v_lshl_add_u64 v[116:117], v[76:77], 0, v[6:7]
	v_lshl_add_u64 v[118:119], v[76:77], 0, v[10:11]
	v_lshl_add_u64 v[120:121], v[76:77], 0, v[14:15]
	flat_load_dwordx4 v[76:79], v[98:99]
	flat_load_dwordx4 v[80:83], v[100:101]
	flat_load_dwordx4 v[84:87], v[102:103]
	flat_load_dwordx4 v[88:91], v[104:105]
	flat_load_dwordx4 v[92:95], v[96:97]
	s_nop 0
	flat_load_dwordx4 v[96:99], v[116:117]
	flat_load_dwordx4 v[100:103], v[118:119]
	flat_load_dwordx4 v[104:107], v[120:121]
	s_add_i32 s16, s16, s40
	s_add_i32 s3, s3, s13
	s_cmpk_gt_i32 s16, 0x7ff
	s_waitcnt vmcnt(0) lgkmcnt(0)
	v_mov_b32_e32 v28, v160
	v_mov_b32_e32 v29, v161
	v_mov_b32_e32 v30, v162
	v_mov_b32_e32 v31, v163
	v_mov_b32_e32 v48, v164
	v_mov_b32_e32 v49, v165
	v_mov_b32_e32 v50, v166
	v_mov_b32_e32 v51, v167
	v_mov_b32_e32 v52, v168
	v_mov_b32_e32 v53, v169
	v_mov_b32_e32 v54, v170
	v_mov_b32_e32 v55, v171
	v_mov_b32_e32 v56, v172
	v_mov_b32_e32 v57, v173
	v_mov_b32_e32 v58, v174
	v_mov_b32_e32 v59, v175
	v_mov_b32_e32 v60, v176
	v_mov_b32_e32 v61, v177
	v_mov_b32_e32 v62, v178
	v_mov_b32_e32 v63, v179
	v_mov_b32_e32 v64, v180
	v_mov_b32_e32 v65, v181
	v_mov_b32_e32 v66, v182
	v_mov_b32_e32 v67, v183
	v_mov_b32_e32 v68, v184
	v_mov_b32_e32 v69, v185
	v_mov_b32_e32 v70, v186
	v_mov_b32_e32 v71, v187
	v_mov_b32_e32 v72, v188
	v_mov_b32_e32 v73, v189
	v_mov_b32_e32 v74, v190
	v_mov_b32_e32 v75, v191
	s_cbranch_scc1 .Lnpf_skip_b
	v_lshl_add_u64 v[156:157], v[156:157], 0, s[98:99]
	v_lshl_add_u64 v[158:159], v[156:157], 0, s[100:101]
	global_load_dwordx4 v[160:163], v[156:157], off nt
	global_load_dwordx4 v[164:167], v[156:157], off offset:1024 nt
	global_load_dwordx4 v[168:171], v[156:157], off offset:2048 nt
	global_load_dwordx4 v[172:175], v[156:157], off offset:3072 nt
	global_load_dwordx4 v[176:179], v[158:159], off nt
	global_load_dwordx4 v[180:183], v[158:159], off offset:1024 nt
	global_load_dwordx4 v[184:187], v[158:159], off offset:2048 nt
	global_load_dwordx4 v[188:191], v[158:159], off offset:3072 nt
.Lnpf_skip_b:
	v_mov_b32_e32 v118, v29
	v_mov_b32_e32 v119, v49
	v_mov_b32_e32 v116, v28
	v_mov_b32_e32 v117, v48
	v_pk_mul_f32 v[118:119], v[118:119], v[118:119]
	v_mov_b32_e32 v120, v30
	v_mov_b32_e32 v126, v53
	v_mov_b32_e32 v127, v57
	v_mov_b32_e32 v124, v52
	v_mov_b32_e32 v125, v56
	v_pk_mul_f32 v[126:127], v[126:127], v[126:127]
	v_mov_b32_e32 v136, v61
	v_mov_b32_e32 v137, v65
	v_mov_b32_e32 v134, v60
	v_mov_b32_e32 v135, v64
	v_mov_b32_e32 v144, v69
	v_mov_b32_e32 v145, v73
	v_pk_fma_f32 v[116:117], v[116:117], v[116:117], v[118:119]
	v_pk_mul_f32 v[118:119], v[136:137], v[136:137]
	v_mov_b32_e32 v121, v50
	v_mov_b32_e32 v128, v54
	v_mov_b32_e32 v129, v58
	v_mov_b32_e32 v138, v62
	v_mov_b32_e32 v139, v66
	v_mov_b32_e32 v142, v68
	v_mov_b32_e32 v143, v72
	v_pk_fma_f32 v[124:125], v[124:125], v[124:125], v[126:127]
	v_pk_mul_f32 v[126:127], v[144:145], v[144:145]
	v_pk_fma_f32 v[118:119], v[134:135], v[134:135], v[118:119]
	v_mov_b32_e32 v122, v31
	v_mov_b32_e32 v123, v51
	v_mov_b32_e32 v140, v63
	v_mov_b32_e32 v141, v67
	v_mov_b32_e32 v146, v70
	v_mov_b32_e32 v147, v74
	v_pk_fma_f32 v[116:117], v[120:121], v[120:121], v[116:117]
	v_pk_fma_f32 v[120:121], v[128:129], v[128:129], v[124:125]
	v_pk_fma_f32 v[124:125], v[142:143], v[142:143], v[126:127]
	v_pk_fma_f32 v[118:119], v[138:139], v[138:139], v[118:119]
	v_mov_b32_e32 v130, v55
	v_mov_b32_e32 v131, v59
	v_mov_b32_e32 v148, v71
	v_mov_b32_e32 v149, v75
	v_pk_fma_f32 v[116:117], v[122:123], v[122:123], v[116:117]
	v_pk_fma_f32 v[122:123], v[146:147], v[146:147], v[124:125]
	v_pk_fma_f32 v[118:119], v[140:141], v[140:141], v[118:119]
	v_pk_fma_f32 v[120:121], v[130:131], v[130:131], v[120:121]
	v_pk_fma_f32 v[122:123], v[148:149], v[148:149], v[122:123]
	v_mov_b32_e32 v125, v116
	v_mov_b32_e32 v124, v118
	v_mov_b32_e32 v116, v119
	v_mov_b32_e32 v127, v120
	v_mov_b32_e32 v126, v122
	v_pk_add_f32 v[116:117], v[124:125], v[116:117]
	v_mov_b32_e32 v120, v123
	v_pk_add_f32 v[116:117], v[116:117], v[126:127]
	v_pk_add_f32 v[76:77], v[76:77], 1.0 op_sel_hi:[1,0]
	v_pk_add_f32 v[116:117], v[116:117], v[120:121]
	ds_bpermute_b32 v119, v133, v117
	ds_bpermute_b32 v118, v133, v116
	v_pk_add_f32 v[78:79], v[78:79], 1.0 op_sel_hi:[1,0]
	v_pk_add_f32 v[80:81], v[80:81], 1.0 op_sel_hi:[1,0]
	v_pk_add_f32 v[82:83], v[82:83], 1.0 op_sel_hi:[1,0]
	v_pk_add_f32 v[84:85], v[84:85], 1.0 op_sel_hi:[1,0]
	s_waitcnt lgkmcnt(0)
	v_pk_add_f32 v[116:117], v[116:117], v[118:119]
	ds_bpermute_b32 v119, v150, v117
	ds_bpermute_b32 v118, v150, v116
	v_pk_add_f32 v[86:87], v[86:87], 1.0 op_sel_hi:[1,0]
	v_pk_add_f32 v[88:89], v[88:89], 1.0 op_sel_hi:[1,0]
	v_pk_add_f32 v[90:91], v[90:91], 1.0 op_sel_hi:[1,0]
	s_waitcnt lgkmcnt(0)
	v_pk_add_f32 v[116:117], v[116:117], v[118:119]
	ds_bpermute_b32 v119, v151, v117
	ds_bpermute_b32 v118, v151, v116
	s_waitcnt lgkmcnt(0)
	v_pk_add_f32 v[116:117], v[116:117], v[118:119]
	ds_bpermute_b32 v119, v152, v117
	ds_bpermute_b32 v118, v152, v116
	s_waitcnt lgkmcnt(0)
	v_pk_add_f32 v[116:117], v[116:117], v[118:119]
	ds_bpermute_b32 v119, v153, v117
	ds_bpermute_b32 v118, v153, v116
	s_waitcnt lgkmcnt(0)
	v_pk_add_f32 v[116:117], v[116:117], v[118:119]
	ds_bpermute_b32 v119, v154, v117
	ds_bpermute_b32 v118, v154, v116
	s_waitcnt lgkmcnt(0)
	v_pk_add_f32 v[116:117], v[116:117], v[118:119]
	s_nop 0
	v_pk_fma_f32 v[116:117], v[116:117], s[12:13], v[2:3] op_sel_hi:[1,0,0]
	s_nop 0
	v_mul_f32_e32 v27, 0x4b800000, v117
	v_cmp_gt_f32_e64 s[4:5], s15, v117
	v_mul_f32_e32 v118, 0x4b800000, v116
	v_cmp_gt_f32_e32 vcc, s15, v116
	v_cndmask_b32_e64 v27, v117, v27, s[4:5]
	v_rsq_f32_e32 v27, v27
	v_cndmask_b32_e32 v116, v116, v118, vcc
	v_rsq_f32_e32 v117, v116
	v_mul_f32_e32 v116, 0x45800000, v27
	v_cndmask_b32_e64 v116, v27, v116, s[4:5]
	v_mul_f32_e32 v118, 0x45800000, v117
	v_cndmask_b32_e32 v118, v117, v118, vcc
	v_pk_mul_f32 v[28:29], v[28:29], v[116:117] op_sel_hi:[1,0]
	v_pk_mul_f32 v[30:31], v[30:31], v[116:117] op_sel_hi:[1,0]
	v_pk_mul_f32 v[60:61], v[60:61], v[118:119] op_sel_hi:[1,0]
	v_pk_mul_f32 v[62:63], v[62:63], v[118:119] op_sel_hi:[1,0]
	v_pk_mul_f32 v[48:49], v[48:49], v[116:117] op_sel_hi:[1,0]
	v_pk_mul_f32 v[50:51], v[50:51], v[116:117] op_sel_hi:[1,0]
	v_pk_mul_f32 v[64:65], v[64:65], v[118:119] op_sel_hi:[1,0]
	v_pk_mul_f32 v[66:67], v[66:67], v[118:119] op_sel_hi:[1,0]
	v_pk_mul_f32 v[52:53], v[52:53], v[116:117] op_sel_hi:[1,0]
	v_pk_mul_f32 v[54:55], v[54:55], v[116:117] op_sel_hi:[1,0]
	v_pk_mul_f32 v[68:69], v[68:69], v[118:119] op_sel_hi:[1,0]
	v_pk_mul_f32 v[70:71], v[70:71], v[118:119] op_sel_hi:[1,0]
	v_pk_mul_f32 v[56:57], v[56:57], v[116:117] op_sel_hi:[1,0]
	v_pk_mul_f32 v[58:59], v[58:59], v[116:117] op_sel_hi:[1,0]
	v_pk_mul_f32 v[72:73], v[72:73], v[118:119] op_sel_hi:[1,0]
	v_pk_mul_f32 v[74:75], v[74:75], v[118:119] op_sel_hi:[1,0]
	v_pk_mul_f32 v[28:29], v[32:33], v[28:29]
	v_pk_mul_f32 v[30:31], v[34:35], v[30:31]
	v_pk_mul_f32 v[32:33], v[32:33], v[60:61]
	v_pk_mul_f32 v[34:35], v[34:35], v[62:63]
	v_pk_mul_f32 v[48:49], v[48:49], v[36:37]
	v_pk_mul_f32 v[50:51], v[50:51], v[38:39]
	v_pk_mul_f32 v[36:37], v[64:65], v[36:37]
	v_pk_mul_f32 v[38:39], v[66:67], v[38:39]
	v_pk_mul_f32 v[52:53], v[52:53], v[40:41]
	v_pk_mul_f32 v[54:55], v[54:55], v[42:43]
	v_pk_mul_f32 v[40:41], v[68:69], v[40:41]
	v_pk_mul_f32 v[42:43], v[70:71], v[42:43]
	v_pk_mul_f32 v[56:57], v[56:57], v[44:45]
	v_pk_mul_f32 v[58:59], v[58:59], v[46:47]
	v_pk_mul_f32 v[44:45], v[72:73], v[44:45]
	v_pk_mul_f32 v[46:47], v[74:75], v[46:47]
	v_pk_fma_f32 v[28:29], v[28:29], v[76:77], v[92:93]
	v_pk_fma_f32 v[30:31], v[30:31], v[78:79], v[94:95]
	v_pk_fma_f32 v[32:33], v[76:77], v[32:33], v[92:93]
	v_pk_fma_f32 v[34:35], v[34:35], v[78:79], v[94:95]
	v_pk_fma_f32 v[48:49], v[48:49], v[80:81], v[96:97]
	v_pk_fma_f32 v[50:51], v[50:51], v[82:83], v[98:99]
	v_pk_fma_f32 v[36:37], v[36:37], v[80:81], v[96:97]
	v_pk_fma_f32 v[38:39], v[38:39], v[82:83], v[98:99]
	v_pk_fma_f32 v[52:53], v[52:53], v[84:85], v[100:101]
	v_pk_fma_f32 v[54:55], v[54:55], v[86:87], v[102:103]
	v_pk_fma_f32 v[40:41], v[40:41], v[84:85], v[100:101]
	v_pk_fma_f32 v[42:43], v[42:43], v[86:87], v[102:103]
	v_pk_fma_f32 v[56:57], v[56:57], v[88:89], v[104:105]
	v_pk_fma_f32 v[58:59], v[58:59], v[90:91], v[106:107]
	v_pk_fma_f32 v[44:45], v[44:45], v[88:89], v[104:105]
	v_pk_fma_f32 v[46:47], v[46:47], v[90:91], v[106:107]
	v_cvt_pk_bf16_f32 v28, v28, v29
	v_cvt_pk_bf16_f32 v29, v30, v31
	v_cvt_pk_bf16_f32 v30, v32, v33
	v_cvt_pk_bf16_f32 v31, v34, v35
	v_cvt_pk_bf16_f32 v32, v48, v49
	v_cvt_pk_bf16_f32 v33, v50, v51
	v_cvt_pk_bf16_f32 v34, v36, v37
	v_cvt_pk_bf16_f32 v35, v38, v39
	v_cvt_pk_bf16_f32 v36, v52, v53
	v_cvt_pk_bf16_f32 v37, v54, v55
	v_cvt_pk_bf16_f32 v38, v40, v41
	v_cvt_pk_bf16_f32 v39, v42, v43
	v_cvt_pk_bf16_f32 v40, v56, v57
	v_cvt_pk_bf16_f32 v41, v58, v59
	v_cvt_pk_bf16_f32 v42, v44, v45
	v_cvt_pk_bf16_f32 v43, v46, v47
	flat_store_dwordx2 v[108:109], v[28:29]
	flat_store_dwordx2 v[108:109], v[30:31] offset:2048
	flat_store_dwordx2 v[110:111], v[32:33]
	flat_store_dwordx2 v[110:111], v[34:35] offset:2048
	flat_store_dwordx2 v[112:113], v[36:37]
	flat_store_dwordx2 v[112:113], v[38:39] offset:2048
	flat_store_dwordx2 v[114:115], v[40:41]
	flat_store_dwordx2 v[114:115], v[42:43] offset:2048
	s_cbranch_scc0 .Lnpf_loop
